# plus prep hyena-transposition loop: 32 conv-tap words of a tile requested at tile start, counted waits keep next tile's rows in flight
# speedup vs baseline: 1.0084x; 1.0029x over previous
; #define LAS __attribute__((address_space(3)))
; __device__ __forceinline__ unsigned pk2(float lo, float hi) { unsigned r; asm("v_cvt_pk_bf16_f32 %0, %1, %2" : "=v"(r) : "v"(lo), "v"(hi)); return r; }
; #define HYP_LOAD(hv_, item_) do { const int ti_ = (item_) / 48, ct_ = (item_) - ti_ * 48; \
;             _Pragma("unroll") for (int u = 0; u < 2; ++u) { const int rowi = (tid >> 3) + 64 * u, bb = rowi >> 6, tt = rowi & 63, ch8 = tid & 7; \
;                 hv_[u] = *(const u32x4*)(H + ((size_t)bb * TPB + CTX + ti_ * 64 + tt) * NPAD + C_HY + ct_ * 64 + ch8 * 8); } } while (0)
; __device__ __forceinline__ void prep_phase(const Params& P, int l, LAS unsigned char* lds) {
;     ...
;         u32x4 chv[2] = {(u32x4){0u, 0u, 0u, 0u}, (u32x4){0u, 0u, 0u, 0u}};
;         if ((int)blockIdx.x < 64 * 48) HYP_LOAD(chv, blockIdx.x);
; #pragma unroll 1
;         for (int item = blockIdx.x; item < 64 * 48; item += G) {
;             const int ti = item / 48, ct = item - ti * 48;
;             u32x4 nhv[2] = {(u32x4){0u, 0u, 0u, 0u}, (u32x4){0u, 0u, 0u, 0u}};
;             if (item + G < 64 * 48) HYP_LOAD(nhv, item + G);
;     ...
;               for (int u = 0; u < 8; ++u) { const int cc = (tid >> 6) + 8 * u, ch = ct * 64 + cc;
;                 const float* cw = P.in[7] + (size_t)l * 3 * 3072 + ch; const float w0 = cw[0], w1 = cw[3072], w2 = cw[6144], bias = P.in[8][l * 3072 + ch];
;                 f32x2 o;
; #pragma unroll
;                 for (int bb = 0; bb < 2; ++bb) { const LAS float* lp = L + (bb * 64 + tt) * 65 + cc;
;                     const float xm = tt > 0 ? lp[-65] : 0.f, xp = tt < 63 ? lp[65] : 0.f; o[bb] = xm * w0 + lp[0] * w1 + xp * w2 + bias; }
;                 ZT[(size_t)ch * 4096 + ti * 64 + tt] = pk2(o[0], o[1]); } }
;             asm volatile("s_waitcnt lgkmcnt(0)" ::: "memory"); __builtin_amdgcn_s_barrier(); asm volatile("" ::: "memory");
;             chv[0] = nhv[0]; chv[1] = nhv[1];
.LBB0_237:
	s_or_b64 exec, exec, s[12:13]
	s_waitcnt vmcnt(0) lgkmcnt(0)
	v_mov_b32_e32 v27, v92
	v_mov_b32_e32 v28, v93
	v_mov_b32_e32 v26, v94
	v_mov_b32_e32 v18, v95
	v_mul_f32_e32 v29, v28, v29
	v_fmac_f32_e32 v29, v27, v13
	v_fmac_f32_e32 v29, v26, v19
	v_pk_mul_f32 v[16:17], v[26:27], v[16:17]
	ds_read_b32 v26, v32 offset:16864
	v_add_u32_e32 v12, 56, v12
	v_ashrrev_i32_e32 v13, 31, v12
	v_lshlrev_b64 v[12:13], 14, v[12:13]
	v_lshl_add_u64 v[12:13], v[14:15], 0, v[12:13]
	s_waitcnt lgkmcnt(0)
	v_fma_f32 v17, v28, v26, v17
	v_add_f32_e32 v16, v16, v17
	v_add_f32_e32 v16, v18, v16
	v_add_f32_e32 v19, v18, v29
	v_cvt_pk_bf16_f32 v16, v19, v16
	global_store_dword v[12:13], v16, off
	s_waitcnt lgkmcnt(0)
	s_barrier
	s_add_i32 s14, s14, s68
	s_and_b64 vcc, exec, s[10:11]
	s_mov_b32 s12, s15
	v_mov_b32_e32 v12, v8
	v_mov_b32_e32 v13, v9
	v_mov_b32_e32 v14, v10
	v_mov_b32_e32 v15, v11
	v_mov_b32_e32 v16, v4
	v_mov_b32_e32 v17, v5
	v_mov_b32_e32 v18, v6
	v_mov_b32_e32 v19, v7
	s_cbranch_vccnz .LBB0_304
.LBB0_238:
	s_mul_hi_i32 s16, s12, 0x2aaaaaab
	s_lshr_b32 s17, s16, 31
	s_ashr_i32 s16, s16, 3
	s_add_i32 s16, s16, s17
	s_mul_i32 s16, s16, 0xfffff400
	s_add_i32 s16, s16, s14
	v_add_u32_e32 v96, s16, v235
	v_ashrrev_i32_e32 v97, 31, v96
	v_lshl_add_u64 v[96:97], v[96:97], 2, s[8:9]
	v_add_co_u32_e32 v98, vcc, 0x3000, v96
	s_nop 1
	v_addc_co_u32_e32 v99, vcc, 0, v97, vcc
	v_add_co_u32_e32 v100, vcc, 0x6000, v96
	s_nop 1
	v_addc_co_u32_e32 v101, vcc, 0, v97, vcc
	v_add_u32_e32 v102, s16, v48
	v_ashrrev_i32_e32 v103, 31, v102
	v_lshl_add_u64 v[102:103], v[102:103], 2, s[52:53]
	global_load_dword v64, v[96:97], off
	global_load_dword v65, v[98:99], off
	global_load_dword v66, v[100:101], off
	global_load_dword v67, v[102:103], off
	global_load_dword v68, v[96:97], off offset:32
	global_load_dword v69, v[98:99], off offset:32
	global_load_dword v70, v[100:101], off offset:32
	global_load_dword v71, v[102:103], off offset:32
	global_load_dword v72, v[96:97], off offset:64
	global_load_dword v73, v[98:99], off offset:64
	global_load_dword v74, v[100:101], off offset:64
	global_load_dword v75, v[102:103], off offset:64
	global_load_dword v76, v[96:97], off offset:96
	global_load_dword v77, v[98:99], off offset:96
	global_load_dword v78, v[100:101], off offset:96
	global_load_dword v79, v[102:103], off offset:96
	global_load_dword v80, v[96:97], off offset:128
	global_load_dword v81, v[98:99], off offset:128
	global_load_dword v82, v[100:101], off offset:128
	global_load_dword v83, v[102:103], off offset:128
	global_load_dword v84, v[96:97], off offset:160
	global_load_dword v85, v[98:99], off offset:160
	global_load_dword v86, v[100:101], off offset:160
	global_load_dword v87, v[102:103], off offset:160
	global_load_dword v88, v[96:97], off offset:192
	global_load_dword v89, v[98:99], off offset:192
	global_load_dword v90, v[100:101], off offset:192
	global_load_dword v91, v[102:103], off offset:192
	global_load_dword v92, v[96:97], off offset:224
	global_load_dword v93, v[98:99], off offset:224
	global_load_dword v94, v[100:101], off offset:224
	global_load_dword v95, v[102:103], off offset:224
	s_add_i32 s15, s12, s49
	s_cmpk_gt_i32 s15, 0xbff
	s_cselect_b64 s[10:11], -1, 0
	v_mov_b32_e32 v51, 0
	s_and_b64 vcc, exec, s[10:11]
	v_mov_b32_e32 v8, 0
	v_mov_b32_e32 v9, 0
	v_mov_b32_e32 v10, 0
	v_mov_b32_e32 v11, 0
	v_mov_b32_e32 v4, 0
	v_mov_b32_e32 v5, 0
	v_mov_b32_e32 v6, 0
	v_mov_b32_e32 v7, 0
	s_cbranch_vccnz .LBB0_240
	s_mul_hi_i32 s13, s15, 0x2aaaaaab
	s_lshr_b32 s16, s13, 31
	s_ashr_i32 s13, s13, 3
	s_add_i32 s13, s13, s16
	s_lshl_b32 s16, s13, 6
	s_ashr_i32 s17, s16, 31
	v_lshl_add_u64 v[4:5], s[16:17], 0, v[20:21]
	v_lshl_add_u64 v[6:7], v[4:5], 0, v[0:1]
	v_mov_b64_e32 v[8:9], s[60:61]
	s_mulk_i32 s13, 0xf400
	s_add_i32 s16, s68, s14
	v_mad_u64_u32 v[10:11], s[18:19], v6, s43, v[8:9]
	s_add_i32 s16, s16, s13
	v_mov_b32_e32 v6, v11
	v_lshl_add_u64 v[4:5], v[4:5], 0, v[24:25]
	s_ashr_i32 s17, s16, 31
	v_mad_u64_u32 v[6:7], s[18:19], v7, s43, v[6:7]
	v_mad_u64_u32 v[8:9], s[18:19], v4, s43, v[8:9]
	v_mov_b32_e32 v11, v6
	s_lshl_b64 s[16:17], s[16:17], 1
	v_mov_b32_e32 v4, v9
	v_lshl_add_u64 v[6:7], v[10:11], 0, s[16:17]
	v_mad_u64_u32 v[4:5], s[18:19], v5, s43, v[4:5]
	v_lshl_add_u64 v[6:7], v[6:7], 0, v[2:3]
	s_movk_i32 s3, 0x4000
	v_mov_b32_e32 v9, v4
	v_add_co_u32_e32 v6, vcc, s3, v6
	v_lshl_add_u64 v[4:5], v[8:9], 0, s[16:17]
	s_nop 0
	v_addc_co_u32_e32 v7, vcc, 0, v7, vcc
	v_lshl_add_u64 v[4:5], v[4:5], 0, v[2:3]
	v_add_co_u32_e32 v8, vcc, 0x4000, v4
	s_nop 1
	v_addc_co_u32_e32 v9, vcc, 0, v5, vcc
	global_load_dwordx4 v[4:7], v[6:7], off offset:64
	s_nop 0
	global_load_dwordx4 v[8:11], v[8:9], off offset:64
; #define LAS __attribute__((address_space(3)))
; __device__ __forceinline__ unsigned pk2(float lo, float hi) { unsigned r; asm("v_cvt_pk_bf16_f32 %0, %1, %2" : "=v"(r) : "v"(lo), "v"(hi)); return r; }
; __device__ __forceinline__ void prep_phase(const Params& P, int l, LAS unsigned char* lds) {
;     ...
;             for (int u = 0; u < 2; ++u) { const int rowi = (tid >> 3) + 64 * u, bb = rowi >> 6, tt = rowi & 63, ch8 = tid & 7;
;                 float f[8]; unpack8(chv[u], f);
; #pragma unroll
;                 for (int e = 0; e < 8; ++e) L[(bb * 64 + tt) * 65 + ch8 * 8 + e] = f[e]; }
;             asm volatile("s_waitcnt lgkmcnt(0)" ::: "memory"); __builtin_amdgcn_s_barrier(); asm volatile("" ::: "memory");
;             { const int tt = tid & 63;
; #pragma unroll
;               for (int u = 0; u < 8; ++u) { const int cc = (tid >> 6) + 8 * u, ch = ct * 64 + cc;
;                 const float* cw = P.in[7] + (size_t)l * 3 * 3072 + ch; const float w0 = cw[0], w1 = cw[3072], w2 = cw[6144], bias = P.in[8][l * 3072 + ch];
;                 f32x2 o;
; #pragma unroll
;                 for (int bb = 0; bb < 2; ++bb) { const LAS float* lp = L + (bb * 64 + tt) * 65 + cc;
;                     const float xm = tt > 0 ? lp[-65] : 0.f, xp = tt < 63 ? lp[65] : 0.f; o[bb] = xm * w0 + lp[0] * w1 + xp * w2 + bias; }
;                 ZT[(size_t)ch * 4096 + ti * 64 + tt] = pk2(o[0], o[1]); } }
.LBB0_240:
	s_mul_hi_i32 s12, s12, 0x2aaaaaab
	s_lshr_b32 s13, s12, 31
	s_ashr_i32 s16, s12, 3
	s_add_i32 s16, s16, s13
	s_waitcnt vmcnt(33)
	v_lshlrev_b32_e32 v26, 16, v16
	v_and_b32_e32 v16, 0xffff0000, v16
	v_add_u32_e32 v50, v30, v31
	s_mul_i32 s12, s16, 0xfffff400
	v_lshlrev_b32_e32 v27, 16, v17
	v_and_b32_e32 v17, 0xffff0000, v17
	v_lshlrev_b32_e32 v28, 16, v18
	v_and_b32_e32 v18, 0xffff0000, v18
	v_lshlrev_b32_e32 v29, 16, v19
	v_and_b32_e32 v19, 0xffff0000, v19
	ds_write2_b32 v50, v26, v16 offset1:1
	ds_write2_b32 v50, v27, v17 offset0:2 offset1:3
	ds_write2_b32 v50, v28, v18 offset0:4 offset1:5
	ds_write2_b32 v50, v29, v19 offset0:6 offset1:7
	s_waitcnt vmcnt(32)
	v_lshlrev_b32_e32 v16, 16, v12
	v_and_b32_e32 v12, 0xffff0000, v12
	s_add_i32 s12, s12, s14
	v_lshlrev_b32_e32 v17, 16, v13
	v_and_b32_e32 v13, 0xffff0000, v13
	v_lshlrev_b32_e32 v18, 16, v14
	v_and_b32_e32 v14, 0xffff0000, v14
	v_lshlrev_b32_e32 v19, 16, v15
	v_and_b32_e32 v15, 0xffff0000, v15
	ds_write2_b32 v49, v16, v12 offset1:1
	ds_write2_b32 v49, v17, v13 offset0:2 offset1:3
	ds_write2_b32 v49, v18, v14 offset0:4 offset1:5
	ds_write2_b32 v49, v19, v15 offset0:6 offset1:7
	v_add_u32_e32 v12, s12, v235
	v_ashrrev_i32_e32 v13, 31, v12
	v_lshl_add_u64 v[16:17], v[12:13], 2, s[8:9]
	v_add_co_u32_e32 v14, vcc, 0x3000, v16
	s_waitcnt lgkmcnt(0)
	s_barrier
	s_nop 0
	v_addc_co_u32_e32 v15, vcc, 0, v17, vcc
	v_add_co_u32_e32 v18, vcc, 0x6000, v16
	s_nop 0
	v_addc_co_u32_e32 v19, vcc, 0, v17, vcc
	v_add_u32_e32 v14, s12, v48
	v_ashrrev_i32_e32 v15, 31, v14
	v_lshl_add_u64 v[18:19], v[14:15], 2, s[52:53]
	s_and_saveexec_b64 s[12:13], s[4:5]
	ds_read_b32 v51, v33
	s_or_b64 exec, exec, s[12:13]
	v_mov_b32_e32 v29, 0
	v_mov_b32_e32 v14, 0
	s_and_saveexec_b64 s[12:13], s[6:7]
	ds_read_b32 v14, v32 offset:260
	s_or_b64 exec, exec, s[12:13]
	ds_read_b32 v15, v32
	s_and_saveexec_b64 s[12:13], s[4:5]
	ds_read_b32 v29, v32 offset:16380
	s_or_b64 exec, exec, s[12:13]
	v_mov_b32_e32 v50, 0
	v_mov_b32_e32 v28, 0
	s_and_saveexec_b64 s[12:13], s[6:7]
	ds_read_b32 v28, v32 offset:16900
	s_or_b64 exec, exec, s[12:13]
	s_waitcnt vmcnt(28) lgkmcnt(0)
	v_mov_b32_e32 v27, v64
	v_mov_b32_e32 v52, v65
	v_mov_b32_e32 v26, v66
	v_mov_b32_e32 v53, v67
	v_mul_f32_e32 v15, v52, v15
	v_fmac_f32_e32 v15, v27, v51
	v_fmac_f32_e32 v15, v26, v14
	v_pk_mul_f32 v[26:27], v[26:27], v[28:29]
	ds_read_b32 v28, v32 offset:16640
	s_lshl_b32 s12, s16, 6
	s_ashr_i32 s13, s12, 31
	v_add_f32_e32 v51, v53, v15
	v_lshl_add_u64 v[14:15], s[12:13], 2, v[22:23]
	s_waitcnt lgkmcnt(0)
	v_fma_f32 v27, v52, v28, v27
	v_add_f32_e32 v26, v26, v27
	v_add_f32_e32 v26, v53, v26
	v_cvt_pk_bf16_f32 v28, v51, v26
	v_lshlrev_b64 v[26:27], 14, v[12:13]
	v_lshl_add_u64 v[26:27], v[14:15], 0, v[26:27]
	global_store_dword v[26:27], v28, off
	v_add_co_u32_e32 v28, vcc, 0x3000, v16
	s_nop 0
	v_addc_co_u32_e32 v29, vcc, 0, v17, vcc
	v_add_co_u32_e32 v28, vcc, 0x6000, v16
	s_nop 1
	v_addc_co_u32_e32 v29, vcc, 0, v17, vcc
	s_and_saveexec_b64 s[12:13], s[4:5]
	ds_read_b32 v50, v35
	s_or_b64 exec, exec, s[12:13]
	v_mov_b32_e32 v29, 0
	v_mov_b32_e32 v53, 0
	s_and_saveexec_b64 s[12:13], s[6:7]
	ds_read_b32 v53, v32 offset:292
	s_or_b64 exec, exec, s[12:13]
	ds_read_b32 v54, v34
	s_and_saveexec_b64 s[12:13], s[4:5]
	ds_read_b32 v29, v32 offset:16412
	s_or_b64 exec, exec, s[12:13]
	v_mov_b32_e32 v13, 0
	v_mov_b32_e32 v28, 0
	s_and_saveexec_b64 s[12:13], s[6:7]
	ds_read_b32 v28, v32 offset:16932
	s_or_b64 exec, exec, s[12:13]
	s_waitcnt vmcnt(24) lgkmcnt(0)
	v_mov_b32_e32 v27, v68
	v_mov_b32_e32 v51, v69
	v_mov_b32_e32 v26, v70
	v_mov_b32_e32 v52, v71
	v_mul_f32_e32 v54, v51, v54
	v_fmac_f32_e32 v54, v27, v50
	v_fmac_f32_e32 v54, v26, v53
	v_pk_mul_f32 v[26:27], v[26:27], v[28:29]
	ds_read_b32 v28, v32 offset:16672
	v_add_f32_e32 v50, v52, v54
	v_add_u32_e32 v54, 8, v12
	v_ashrrev_i32_e32 v55, 31, v54
	s_waitcnt lgkmcnt(0)
	v_fma_f32 v27, v51, v28, v27
	v_add_f32_e32 v26, v26, v27
	v_add_f32_e32 v26, v52, v26
	v_cvt_pk_bf16_f32 v28, v50, v26
	v_lshlrev_b64 v[26:27], 14, v[54:55]
	v_lshl_add_u64 v[26:27], v[14:15], 0, v[26:27]
	global_store_dword v[26:27], v28, off
	v_add_co_u32_e32 v28, vcc, 0x3000, v16
	s_nop 0
	v_addc_co_u32_e32 v29, vcc, 0, v17, vcc
	v_add_co_u32_e32 v28, vcc, 0x6000, v16
	s_nop 1
	v_addc_co_u32_e32 v29, vcc, 0, v17, vcc
	s_and_saveexec_b64 s[12:13], s[4:5]
	ds_read_b32 v13, v37
	s_or_b64 exec, exec, s[12:13]
	v_mov_b32_e32 v29, 0
	v_mov_b32_e32 v53, 0
	s_and_saveexec_b64 s[12:13], s[6:7]
	ds_read_b32 v53, v32 offset:324
	s_or_b64 exec, exec, s[12:13]
	ds_read_b32 v54, v36
	s_and_saveexec_b64 s[12:13], s[4:5]
	ds_read_b32 v29, v32 offset:16444
	s_or_b64 exec, exec, s[12:13]
	v_mov_b32_e32 v50, 0
	v_mov_b32_e32 v28, 0
	s_and_saveexec_b64 s[12:13], s[6:7]
	ds_read_b32 v28, v32 offset:16964
	s_or_b64 exec, exec, s[12:13]
	s_waitcnt vmcnt(20) lgkmcnt(0)
	v_mov_b32_e32 v27, v72
	v_mov_b32_e32 v51, v73
	v_mov_b32_e32 v26, v74
	v_mov_b32_e32 v52, v75
	v_mul_f32_e32 v54, v51, v54
	v_fmac_f32_e32 v54, v27, v13
	v_fmac_f32_e32 v54, v26, v53
	v_pk_mul_f32 v[26:27], v[26:27], v[28:29]
	ds_read_b32 v28, v32 offset:16704
	v_add_f32_e32 v13, v52, v54
	v_add_u32_e32 v54, 16, v12
	v_ashrrev_i32_e32 v55, 31, v54
	s_waitcnt lgkmcnt(0)
; #define LAS __attribute__((address_space(3)))
; __device__ __forceinline__ unsigned pk2(float lo, float hi) { unsigned r; asm("v_cvt_pk_bf16_f32 %0, %1, %2" : "=v"(r) : "v"(lo), "v"(hi)); return r; }
; __device__ __forceinline__ void prep_phase(const Params& P, int l, LAS unsigned char* lds) {
;     ...
;               for (int u = 0; u < 8; ++u) { const int cc = (tid >> 6) + 8 * u, ch = ct * 64 + cc;
;                 const float* cw = P.in[7] + (size_t)l * 3 * 3072 + ch; const float w0 = cw[0], w1 = cw[3072], w2 = cw[6144], bias = P.in[8][l * 3072 + ch];
;                 f32x2 o;
; #pragma unroll
;                 for (int bb = 0; bb < 2; ++bb) { const LAS float* lp = L + (bb * 64 + tt) * 65 + cc;
;                     const float xm = tt > 0 ? lp[-65] : 0.f, xp = tt < 63 ? lp[65] : 0.f; o[bb] = xm * w0 + lp[0] * w1 + xp * w2 + bias; }
;                 ZT[(size_t)ch * 4096 + ti * 64 + tt] = pk2(o[0], o[1]); } }
	v_fma_f32 v27, v51, v28, v27
	v_add_f32_e32 v26, v26, v27
	v_add_f32_e32 v26, v52, v26
	v_cvt_pk_bf16_f32 v13, v13, v26
	v_lshlrev_b64 v[26:27], 14, v[54:55]
	v_add_co_u32_e32 v28, vcc, 0x3000, v16
	v_lshl_add_u64 v[26:27], v[14:15], 0, v[26:27]
	s_nop 0
	v_addc_co_u32_e32 v29, vcc, 0, v17, vcc
	global_store_dword v[26:27], v13, off
	s_nop 0
	v_add_co_u32_e32 v28, vcc, 0x6000, v16
	s_nop 1
	v_addc_co_u32_e32 v29, vcc, 0, v17, vcc
	s_and_saveexec_b64 s[12:13], s[4:5]
	ds_read_b32 v50, v39
	s_or_b64 exec, exec, s[12:13]
	v_mov_b32_e32 v29, 0
	v_mov_b32_e32 v53, 0
	s_and_saveexec_b64 s[12:13], s[6:7]
	ds_read_b32 v53, v32 offset:356
	s_or_b64 exec, exec, s[12:13]
	ds_read_b32 v54, v38
	s_and_saveexec_b64 s[12:13], s[4:5]
	ds_read_b32 v29, v32 offset:16476
	s_or_b64 exec, exec, s[12:13]
	v_mov_b32_e32 v13, 0
	v_mov_b32_e32 v28, 0
	s_and_saveexec_b64 s[12:13], s[6:7]
	ds_read_b32 v28, v32 offset:16996
	s_or_b64 exec, exec, s[12:13]
	s_waitcnt vmcnt(16) lgkmcnt(0)
	v_mov_b32_e32 v27, v76
	v_mov_b32_e32 v51, v77
	v_mov_b32_e32 v26, v78
	v_mov_b32_e32 v52, v79
	v_mul_f32_e32 v54, v51, v54
	v_fmac_f32_e32 v54, v27, v50
	v_fmac_f32_e32 v54, v26, v53
	v_pk_mul_f32 v[26:27], v[26:27], v[28:29]
	ds_read_b32 v28, v32 offset:16736
	v_add_f32_e32 v50, v52, v54
	v_add_u32_e32 v54, 24, v12
	v_ashrrev_i32_e32 v55, 31, v54
	s_waitcnt lgkmcnt(0)
	v_fma_f32 v27, v51, v28, v27
	v_add_f32_e32 v26, v26, v27
	v_add_f32_e32 v26, v52, v26
	v_cvt_pk_bf16_f32 v28, v50, v26
	v_lshlrev_b64 v[26:27], 14, v[54:55]
	v_lshl_add_u64 v[26:27], v[14:15], 0, v[26:27]
	global_store_dword v[26:27], v28, off
	v_add_co_u32_e32 v28, vcc, 0x3000, v16
	s_nop 0
	v_addc_co_u32_e32 v29, vcc, 0, v17, vcc
	v_add_co_u32_e32 v28, vcc, 0x6000, v16
	s_nop 1
	v_addc_co_u32_e32 v29, vcc, 0, v17, vcc
	s_and_saveexec_b64 s[12:13], s[4:5]
	ds_read_b32 v13, v41
	s_or_b64 exec, exec, s[12:13]
	v_mov_b32_e32 v29, 0
	v_mov_b32_e32 v53, 0
	s_and_saveexec_b64 s[12:13], s[6:7]
	ds_read_b32 v53, v32 offset:388
	s_or_b64 exec, exec, s[12:13]
	ds_read_b32 v54, v40
	s_and_saveexec_b64 s[12:13], s[4:5]
	ds_read_b32 v29, v32 offset:16508
	s_or_b64 exec, exec, s[12:13]
	v_mov_b32_e32 v50, 0
	v_mov_b32_e32 v28, 0
	s_and_saveexec_b64 s[12:13], s[6:7]
	ds_read_b32 v28, v32 offset:17028
	s_or_b64 exec, exec, s[12:13]
	s_waitcnt vmcnt(12) lgkmcnt(0)
	v_mov_b32_e32 v27, v80
	v_mov_b32_e32 v51, v81
	v_mov_b32_e32 v26, v82
	v_mov_b32_e32 v52, v83
	v_mul_f32_e32 v54, v51, v54
	v_fmac_f32_e32 v54, v27, v13
	v_fmac_f32_e32 v54, v26, v53
	v_pk_mul_f32 v[26:27], v[26:27], v[28:29]
	ds_read_b32 v28, v32 offset:16768
	v_add_f32_e32 v13, v52, v54
	v_add_u32_e32 v54, 32, v12
	v_ashrrev_i32_e32 v55, 31, v54
	s_waitcnt lgkmcnt(0)
	v_fma_f32 v27, v51, v28, v27
	v_add_f32_e32 v26, v26, v27
	v_add_f32_e32 v26, v52, v26
	v_cvt_pk_bf16_f32 v13, v13, v26
	v_lshlrev_b64 v[26:27], 14, v[54:55]
	v_add_co_u32_e32 v28, vcc, 0x3000, v16
	v_lshl_add_u64 v[26:27], v[14:15], 0, v[26:27]
	s_nop 0
	v_addc_co_u32_e32 v29, vcc, 0, v17, vcc
	global_store_dword v[26:27], v13, off
	s_nop 0
	v_add_co_u32_e32 v28, vcc, 0x6000, v16
	s_nop 1
	v_addc_co_u32_e32 v29, vcc, 0, v17, vcc
	s_and_saveexec_b64 s[12:13], s[4:5]
	ds_read_b32 v50, v43
	s_or_b64 exec, exec, s[12:13]
	v_mov_b32_e32 v29, 0
	v_mov_b32_e32 v53, 0
	s_and_saveexec_b64 s[12:13], s[6:7]
	ds_read_b32 v53, v32 offset:420
	s_or_b64 exec, exec, s[12:13]
	ds_read_b32 v54, v42
	s_and_saveexec_b64 s[12:13], s[4:5]
	ds_read_b32 v29, v32 offset:16540
	s_or_b64 exec, exec, s[12:13]
	v_mov_b32_e32 v51, 0
	v_mov_b32_e32 v28, 0
	s_and_saveexec_b64 s[12:13], s[6:7]
	ds_read_b32 v28, v32 offset:17060
	s_or_b64 exec, exec, s[12:13]
	s_waitcnt vmcnt(8) lgkmcnt(0)
	v_mov_b32_e32 v27, v84
	v_mov_b32_e32 v13, v85
	v_mov_b32_e32 v26, v86
	v_mov_b32_e32 v52, v87
	v_mul_f32_e32 v54, v13, v54
	v_fmac_f32_e32 v54, v27, v50
	v_fmac_f32_e32 v54, v26, v53
	v_pk_mul_f32 v[26:27], v[26:27], v[28:29]
	ds_read_b32 v28, v32 offset:16800
	v_add_f32_e32 v50, v52, v54
	v_add_u32_e32 v54, 40, v12
	v_ashrrev_i32_e32 v55, 31, v54
	s_waitcnt lgkmcnt(0)
	v_fma_f32 v13, v13, v28, v27
	v_add_f32_e32 v13, v26, v13
	v_lshlrev_b64 v[26:27], 14, v[54:55]
	v_add_co_u32_e32 v28, vcc, 0x3000, v16
	v_add_f32_e32 v13, v52, v13
	v_lshl_add_u64 v[26:27], v[14:15], 0, v[26:27]
	v_addc_co_u32_e32 v29, vcc, 0, v17, vcc
	v_cvt_pk_bf16_f32 v13, v50, v13
	global_store_dword v[26:27], v13, off
	s_nop 0
	v_add_co_u32_e32 v28, vcc, 0x6000, v16
	s_nop 1
	v_addc_co_u32_e32 v29, vcc, 0, v17, vcc
	s_and_saveexec_b64 s[12:13], s[4:5]
	ds_read_b32 v51, v45
	s_or_b64 exec, exec, s[12:13]
	v_mov_b32_e32 v29, 0
	v_mov_b32_e32 v53, 0
	s_and_saveexec_b64 s[12:13], s[6:7]
	ds_read_b32 v53, v32 offset:452
	s_or_b64 exec, exec, s[12:13]
	ds_read_b32 v54, v44
	s_and_saveexec_b64 s[12:13], s[4:5]
	ds_read_b32 v29, v32 offset:16572
	s_or_b64 exec, exec, s[12:13]
	v_mov_b32_e32 v13, 0
	v_mov_b32_e32 v28, 0
	s_and_saveexec_b64 s[12:13], s[6:7]
	ds_read_b32 v28, v32 offset:17092
	s_or_b64 exec, exec, s[12:13]
	s_waitcnt vmcnt(4) lgkmcnt(0)
	v_mov_b32_e32 v27, v88
	v_mov_b32_e32 v50, v89
	v_mov_b32_e32 v26, v90
	v_mov_b32_e32 v52, v91
	v_mul_f32_e32 v54, v50, v54
	v_fmac_f32_e32 v54, v27, v51
	v_fmac_f32_e32 v54, v26, v53
	v_pk_mul_f32 v[26:27], v[26:27], v[28:29]
	ds_read_b32 v28, v32 offset:16832
	v_add_f32_e32 v51, v52, v54
	v_add_u32_e32 v54, 48, v12
	v_ashrrev_i32_e32 v55, 31, v54
	s_waitcnt lgkmcnt(0)
	v_fma_f32 v27, v50, v28, v27
	v_add_f32_e32 v26, v26, v27
	v_add_f32_e32 v26, v52, v26
	v_cvt_pk_bf16_f32 v28, v51, v26
	v_lshlrev_b64 v[26:27], 14, v[54:55]
	v_lshl_add_u64 v[26:27], v[14:15], 0, v[26:27]
	global_store_dword v[26:27], v28, off
	v_add_co_u32_e32 v28, vcc, 0x3000, v16
	s_nop 0
	v_addc_co_u32_e32 v29, vcc, 0, v17, vcc
	v_add_co_u32_e32 v16, vcc, 0x6000, v16
	s_nop 1
	v_addc_co_u32_e32 v17, vcc, 0, v17, vcc
	s_nop 0
	s_and_saveexec_b64 s[12:13], s[4:5]
	ds_read_b32 v13, v47
	s_or_b64 exec, exec, s[12:13]
	v_mov_b32_e32 v17, 0
	v_mov_b32_e32 v19, 0
	s_and_saveexec_b64 s[12:13], s[6:7]
	s_cbranch_execz .LBB0_301
	ds_read_b32 v19, v32 offset:484
	s_or_b64 exec, exec, s[12:13]
	ds_read_b32 v29, v46
	s_and_saveexec_b64 s[12:13], s[4:5]
	s_cbranch_execnz .LBB0_302
